# FF1 epilogue staged through LDS: 16 coalesced dwordx4 row stores per wave instead of 32 scattered dwordx2
# speedup vs baseline: 1.0443x; 1.0096x over previous
; template <bool RELU2>
; DI void phase_gemm_plain(const bf16_t* X, int K, const bf16_t* W, int N, bf16_t* out, char* lds) {
;     ...
;     for (int ai = 0; ai < 2; ++ai)
; #pragma unroll
;       for (int bj = 0; bj < 2; ++bj)
; #pragma unroll
;         for (int m = 0; m < 4; ++m)
; #pragma unroll
;           for (int q = 0; q < 2; ++q) {
;             float a = acc[ai][bj][m][q][0], b = acc[ai][bj][m][q][1], c = acc[ai][bj][m][q][2], d = acc[ai][bj][m][q][3];
;             if (RELU2) { a = fmaxf(a, 0.f); a *= a; b = fmaxf(b, 0.f); b *= b; c = fmaxf(c, 0.f); c *= c; d = fmaxf(d, 0.f); d *= d; }
;             const int tok = mt * 256 + bj * 128 + wc * 32 + q * 16 + fr, n = nt * 256 + ai * 128 + wr * 64 + m * 16 + fq * 4;
;             store_bf4(out + (size_t)tok * N + n, a, b, c, d);
;           }
.LBB0_349:
	v_and_b32_e32 v190, 15, v162
	v_bfe_u32 v191, v162, 6, 2
	v_lshl_or_b32 v190, v191, 5, v190
	v_mul_u32_u24_e32 v190, 0x210, v190
	v_lshrrev_b32_e32 v191, 8, v162
	v_bfe_u32 v192, v162, 4, 2
	v_lshlrev_b32_e32 v191, 7, v191
	v_lshl_or_b32 v191, v192, 3, v191
	v_add_u32_e32 v190, v190, v191
	v_add_u32_e32 v191, 0x2100, v190
	v_add_u32_e32 v192, 0x10800, v190
	v_add_u32_e32 v193, 0x12900, v190
	v_lshrrev_b32_e32 v194, 6, v162
	v_bfe_u32 v195, v162, 5, 1
	v_lshl_or_b32 v194, v194, 5, v195
	v_and_b32_e32 v195, 31, v162
	v_lshlrev_b32_e32 v195, 4, v195
	s_lshl_b32 s12, s80, 8
	v_add_u32_e32 v196, s12, v194
	v_lshlrev_b32_e32 v196, 13, v196
	s_lshl_b32 s12, s8, 9
	v_add3_u32 v196, v196, s12, v195
	v_mov_b32_e32 v197, 0
	v_readlane_b32 s82, v254, 22
	v_readlane_b32 s83, v254, 23
	v_mul_u32_u24_e32 v194, 0x210, v194
	v_add_u32_e32 v194, v194, v195
	s_mov_b32 s24, 0x4000
	s_mov_b32 s25, 0
	s_nop 1
	v_lshl_add_u64 v[196:197], s[82:83], 0, v[196:197]
	v_max_f32_e32 v124, v124, v124
	v_max_f32_e32 v125, v125, v125
	v_max_f32_e32 v124, 0, v124
	v_max_f32_e32 v125, 0, v125
	v_mov_b32_e32 v129, v162
	v_mov_b32_e32 v130, v162
	v_pk_mul_f32 v[132:133], v[124:125], v[124:125]
	v_max_f32_e32 v124, v126, v126
	v_max_f32_e32 v125, v127, v127
	v_max_f32_e32 v124, 0, v124
	v_lshrrev_b32_e32 v131, 1, v130
	v_max_f32_e32 v125, 0, v125
	v_max_f32_e32 v120, v120, v120
	v_max_f32_e32 v121, v121, v121
	v_and_b32_e32 v128, 15, v129
	s_lshl_b32 s1, s80, 8
	v_and_b32_e32 v131, 0x60, v131
	v_pk_mul_f32 v[126:127], v[124:125], v[124:125]
	v_max_f32_e32 v120, 0, v120
	v_max_f32_e32 v121, 0, v121
	v_or3_b32 v128, v131, s1, v128
	s_lshl_b32 s1, s8, 8
	v_ashrrev_i32_e32 v130, 2, v130
	v_lshrrev_b32_e32 v129, 2, v129
	v_cvt_pk_bf16_f32 v132, v132, v133
	v_cvt_pk_bf16_f32 v133, v126, v127
	v_pk_mul_f32 v[126:127], v[120:121], v[120:121]
	v_max_f32_e32 v120, v122, v122
	v_max_f32_e32 v121, v123, v123
	v_and_b32_e32 v130, 0xffffffc0, v130
	v_and_or_b32 v129, v129, 12, s1
	v_max_f32_e32 v120, 0, v120
	v_max_f32_e32 v121, 0, v121
	v_add_u32_e32 v130, v129, v130
	v_readlane_b32 s8, v254, 22
	v_pk_mul_f32 v[122:123], v[120:121], v[120:121]
	v_or_b32_e32 v120, 16, v128
	v_max_f32_e32 v96, v96, v96
	v_max_f32_e32 v97, v97, v97
	v_max_f32_e32 v98, v98, v98
	v_max_f32_e32 v99, v99, v99
	v_ashrrev_i32_e32 v131, 31, v130
	v_readlane_b32 s9, v254, 23
	v_ashrrev_i32_e32 v121, 31, v120
	v_max_f32_e32 v96, 0, v96
	v_max_f32_e32 v97, 0, v97
	v_max_f32_e32 v98, 0, v98
	v_max_f32_e32 v99, 0, v99
	v_max_f32_e32 v92, v92, v92
	v_max_f32_e32 v93, v93, v93
	v_lshl_add_u64 v[130:131], v[130:131], 1, s[8:9]
	v_lshlrev_b64 v[120:121], 13, v[120:121]
	v_pk_mul_f32 v[96:97], v[96:97], v[96:97]
	v_pk_mul_f32 v[98:99], v[98:99], v[98:99]
	v_max_f32_e32 v92, 0, v92
	v_max_f32_e32 v93, 0, v93
	v_lshl_add_u64 v[120:121], v[130:131], 0, v[120:121]
	v_cvt_pk_bf16_f32 v96, v96, v97
	v_cvt_pk_bf16_f32 v97, v98, v99
	v_pk_mul_f32 v[98:99], v[92:93], v[92:93]
	v_max_f32_e32 v92, v94, v94
	v_max_f32_e32 v93, v95, v95
	ds_write_b64 v191, v[96:97] offset:96
	v_or_b32_e32 v96, 0x80, v128
	v_max_f32_e32 v92, 0, v92
	v_max_f32_e32 v93, 0, v93
	v_max_f32_e32 v88, v88, v88
	v_max_f32_e32 v89, v89, v89
	v_pk_mul_f32 v[94:95], v[92:93], v[92:93]
	v_ashrrev_i32_e32 v97, 31, v96
	v_max_f32_e32 v88, 0, v88
	v_max_f32_e32 v89, 0, v89
	v_lshlrev_b64 v[92:93], 13, v[96:97]
	v_cvt_pk_bf16_f32 v97, v94, v95
	v_pk_mul_f32 v[94:95], v[88:89], v[88:89]
	v_max_f32_e32 v88, v90, v90
	v_max_f32_e32 v89, v91, v91
	v_max_f32_e32 v88, 0, v88
	v_max_f32_e32 v89, 0, v89
	v_max_f32_e32 v116, v116, v116
	v_max_f32_e32 v117, v117, v117
	v_max_f32_e32 v118, v118, v118
	v_max_f32_e32 v119, v119, v119
	v_max_f32_e32 v112, v112, v112
	v_max_f32_e32 v113, v113, v113
	v_max_f32_e32 v114, v114, v114
	v_max_f32_e32 v115, v115, v115
	v_max_f32_e32 v108, v108, v108
	v_max_f32_e32 v109, v109, v109
	v_max_f32_e32 v110, v110, v110
	v_max_f32_e32 v111, v111, v111
	v_max_f32_e32 v104, v104, v104
	v_max_f32_e32 v105, v105, v105
	v_max_f32_e32 v106, v106, v106
	v_max_f32_e32 v107, v107, v107
	v_max_f32_e32 v100, v100, v100
	v_max_f32_e32 v101, v101, v101
	v_max_f32_e32 v102, v102, v102
	v_max_f32_e32 v103, v103, v103
	v_pk_mul_f32 v[90:91], v[88:89], v[88:89]
	v_or_b32_e32 v88, 0x90, v128
	v_max_f32_e32 v84, v84, v84
	v_max_f32_e32 v85, v85, v85
	v_max_f32_e32 v86, v86, v86
	v_max_f32_e32 v87, v87, v87
	v_max_f32_e32 v80, v80, v80
	v_max_f32_e32 v81, v81, v81
	v_max_f32_e32 v82, v82, v82
	v_max_f32_e32 v83, v83, v83
	v_max_f32_e32 v76, v76, v76
	v_max_f32_e32 v77, v77, v77
	v_max_f32_e32 v78, v78, v78
	v_max_f32_e32 v79, v79, v79
	v_max_f32_e32 v72, v72, v72
	v_max_f32_e32 v73, v73, v73
	v_max_f32_e32 v74, v74, v74
	v_max_f32_e32 v75, v75, v75
	v_max_f32_e32 v68, v68, v68
	v_max_f32_e32 v69, v69, v69
	v_max_f32_e32 v70, v70, v70
	v_max_f32_e32 v71, v71, v71
	v_max_f32_e32 v64, v64, v64
	v_max_f32_e32 v65, v65, v65
	v_max_f32_e32 v66, v66, v66
	v_max_f32_e32 v67, v67, v67
	v_max_f32_e32 v60, v60, v60
	v_max_f32_e32 v61, v61, v61
	v_max_f32_e32 v62, v62, v62
	v_max_f32_e32 v63, v63, v63
	v_max_f32_e32 v56, v56, v56
	v_max_f32_e32 v57, v57, v57
	v_max_f32_e32 v58, v58, v58
	v_max_f32_e32 v59, v59, v59
	v_max_f32_e32 v52, v52, v52
	v_max_f32_e32 v53, v53, v53
	v_max_f32_e32 v54, v54, v54
	v_max_f32_e32 v55, v55, v55
	v_max_f32_e32 v48, v48, v48
	v_max_f32_e32 v49, v49, v49
	v_max_f32_e32 v50, v50, v50
	v_max_f32_e32 v51, v51, v51
	v_max_f32_e32 v44, v44, v44
	v_max_f32_e32 v45, v45, v45
	v_max_f32_e32 v46, v46, v46
	v_max_f32_e32 v47, v47, v47
	v_max_f32_e32 v40, v40, v40
	v_max_f32_e32 v41, v41, v41
	v_max_f32_e32 v42, v42, v42
	v_max_f32_e32 v43, v43, v43
; template <bool RELU2>
; DI void phase_gemm_plain(const bf16_t* X, int K, const bf16_t* W, int N, bf16_t* out, char* lds) {
;     ...
;             float a = acc[ai][bj][m][q][0], b = acc[ai][bj][m][q][1], c = acc[ai][bj][m][q][2], d = acc[ai][bj][m][q][3];
;             if (RELU2) { a = fmaxf(a, 0.f); a *= a; b = fmaxf(b, 0.f); b *= b; c = fmaxf(c, 0.f); c *= c; d = fmaxf(d, 0.f); d *= d; }
	v_max_f32_e32 v36, v36, v36
	v_max_f32_e32 v37, v37, v37
	v_max_f32_e32 v38, v38, v38
	v_max_f32_e32 v39, v39, v39
	v_max_f32_e32 v32, v32, v32
	v_max_f32_e32 v33, v33, v33
	v_max_f32_e32 v34, v34, v34
	v_max_f32_e32 v35, v35, v35
	v_max_f32_e32 v28, v28, v28
	v_max_f32_e32 v29, v29, v29
	v_max_f32_e32 v30, v30, v30
	v_max_f32_e32 v31, v31, v31
	v_max_f32_e32 v24, v24, v24
	v_max_f32_e32 v25, v25, v25
	v_max_f32_e32 v26, v26, v26
	v_max_f32_e32 v27, v27, v27
	v_max_f32_e32 v20, v20, v20
	v_max_f32_e32 v21, v21, v21
	v_max_f32_e32 v22, v22, v22
	v_max_f32_e32 v23, v23, v23
	v_max_f32_e32 v16, v16, v16
	v_max_f32_e32 v17, v17, v17
	v_max_f32_e32 v18, v18, v18
	v_max_f32_e32 v19, v19, v19
	v_max_f32_e32 v12, v12, v12
	v_max_f32_e32 v13, v13, v13
	v_max_f32_e32 v14, v14, v14
	v_max_f32_e32 v15, v15, v15
	v_max_f32_e32 v8, v8, v8
	v_max_f32_e32 v9, v9, v9
	v_max_f32_e32 v10, v10, v10
	v_max_f32_e32 v11, v11, v11
	v_max_f32_e32 v4, v4, v4
	v_max_f32_e32 v5, v5, v5
	v_max_f32_e32 v6, v6, v6
	v_max_f32_e32 v7, v7, v7
	v_max_f32_e32 v0, v0, v0
	v_max_f32_e32 v1, v1, v1
	v_max_f32_e32 v2, v2, v2
	v_max_f32_e32 v3, v3, v3
	v_ashrrev_i32_e32 v129, 31, v128
	v_max_f32_e32 v116, 0, v116
	v_max_f32_e32 v117, 0, v117
	v_max_f32_e32 v118, 0, v118
	v_max_f32_e32 v119, 0, v119
	v_max_f32_e32 v112, 0, v112
	v_max_f32_e32 v113, 0, v113
	v_max_f32_e32 v114, 0, v114
	v_max_f32_e32 v115, 0, v115
	v_max_f32_e32 v108, 0, v108
	v_max_f32_e32 v109, 0, v109
	v_max_f32_e32 v110, 0, v110
	v_max_f32_e32 v111, 0, v111
	v_max_f32_e32 v104, 0, v104
	v_max_f32_e32 v105, 0, v105
	v_max_f32_e32 v106, 0, v106
	v_max_f32_e32 v107, 0, v107
	v_max_f32_e32 v100, 0, v100
	v_max_f32_e32 v101, 0, v101
	v_max_f32_e32 v102, 0, v102
	v_max_f32_e32 v103, 0, v103
	v_ashrrev_i32_e32 v89, 31, v88
	v_max_f32_e32 v84, 0, v84
	v_max_f32_e32 v85, 0, v85
	v_max_f32_e32 v86, 0, v86
	v_max_f32_e32 v87, 0, v87
	v_max_f32_e32 v80, 0, v80
	v_max_f32_e32 v81, 0, v81
	v_max_f32_e32 v82, 0, v82
	v_max_f32_e32 v83, 0, v83
	v_max_f32_e32 v76, 0, v76
	v_max_f32_e32 v77, 0, v77
	v_max_f32_e32 v78, 0, v78
	v_max_f32_e32 v79, 0, v79
	v_max_f32_e32 v72, 0, v72
	v_max_f32_e32 v73, 0, v73
	v_max_f32_e32 v74, 0, v74
	v_max_f32_e32 v75, 0, v75
	v_max_f32_e32 v68, 0, v68
	v_max_f32_e32 v69, 0, v69
	v_max_f32_e32 v70, 0, v70
	v_max_f32_e32 v71, 0, v71
	v_max_f32_e32 v64, 0, v64
	v_max_f32_e32 v65, 0, v65
	v_max_f32_e32 v66, 0, v66
	v_max_f32_e32 v67, 0, v67
	v_max_f32_e32 v60, 0, v60
	v_max_f32_e32 v61, 0, v61
	v_max_f32_e32 v62, 0, v62
	v_max_f32_e32 v63, 0, v63
	v_max_f32_e32 v56, 0, v56
	v_max_f32_e32 v57, 0, v57
	v_max_f32_e32 v58, 0, v58
	v_max_f32_e32 v59, 0, v59
	v_max_f32_e32 v52, 0, v52
	v_max_f32_e32 v53, 0, v53
	v_max_f32_e32 v54, 0, v54
	v_max_f32_e32 v55, 0, v55
	v_max_f32_e32 v48, 0, v48
	v_max_f32_e32 v49, 0, v49
	v_max_f32_e32 v50, 0, v50
	v_max_f32_e32 v51, 0, v51
	v_max_f32_e32 v44, 0, v44
	v_max_f32_e32 v45, 0, v45
	v_max_f32_e32 v46, 0, v46
	v_max_f32_e32 v47, 0, v47
	v_max_f32_e32 v40, 0, v40
	v_max_f32_e32 v41, 0, v41
	v_max_f32_e32 v42, 0, v42
	v_max_f32_e32 v43, 0, v43
	v_max_f32_e32 v36, 0, v36
	v_max_f32_e32 v37, 0, v37
	v_max_f32_e32 v38, 0, v38
	v_max_f32_e32 v39, 0, v39
	v_max_f32_e32 v32, 0, v32
	v_max_f32_e32 v33, 0, v33
	v_max_f32_e32 v34, 0, v34
	v_max_f32_e32 v35, 0, v35
	v_max_f32_e32 v28, 0, v28
	v_max_f32_e32 v29, 0, v29
	v_max_f32_e32 v30, 0, v30
	v_max_f32_e32 v31, 0, v31
	v_max_f32_e32 v24, 0, v24
	v_max_f32_e32 v25, 0, v25
	v_max_f32_e32 v26, 0, v26
	v_max_f32_e32 v27, 0, v27
	v_max_f32_e32 v20, 0, v20
	v_max_f32_e32 v21, 0, v21
	v_max_f32_e32 v22, 0, v22
	v_max_f32_e32 v23, 0, v23
	v_max_f32_e32 v16, 0, v16
	v_max_f32_e32 v17, 0, v17
	v_max_f32_e32 v18, 0, v18
	v_max_f32_e32 v19, 0, v19
	v_max_f32_e32 v12, 0, v12
	v_max_f32_e32 v13, 0, v13
	v_max_f32_e32 v14, 0, v14
	v_max_f32_e32 v15, 0, v15
	v_max_f32_e32 v8, 0, v8
	v_max_f32_e32 v9, 0, v9
	v_max_f32_e32 v10, 0, v10
	v_max_f32_e32 v11, 0, v11
	v_max_f32_e32 v4, 0, v4
	v_max_f32_e32 v5, 0, v5
	v_max_f32_e32 v6, 0, v6
	v_max_f32_e32 v7, 0, v7
	v_max_f32_e32 v0, 0, v0
	v_max_f32_e32 v1, 0, v1
	v_max_f32_e32 v2, 0, v2
	v_max_f32_e32 v3, 0, v3
	v_lshlrev_b64 v[124:125], 13, v[128:129]
	v_pk_mul_f32 v[116:117], v[116:117], v[116:117]
	v_pk_mul_f32 v[118:119], v[118:119], v[118:119]
	v_pk_mul_f32 v[112:113], v[112:113], v[112:113]
	v_pk_mul_f32 v[114:115], v[114:115], v[114:115]
	v_pk_mul_f32 v[108:109], v[108:109], v[108:109]
	v_pk_mul_f32 v[110:111], v[110:111], v[110:111]
	v_pk_mul_f32 v[104:105], v[104:105], v[104:105]
	v_pk_mul_f32 v[106:107], v[106:107], v[106:107]
	v_pk_mul_f32 v[100:101], v[100:101], v[100:101]
	v_pk_mul_f32 v[102:103], v[102:103], v[102:103]
	v_lshlrev_b64 v[88:89], 13, v[88:89]
	v_pk_mul_f32 v[84:85], v[84:85], v[84:85]
	v_pk_mul_f32 v[86:87], v[86:87], v[86:87]
	v_pk_mul_f32 v[80:81], v[80:81], v[80:81]
	v_pk_mul_f32 v[82:83], v[82:83], v[82:83]
	v_pk_mul_f32 v[76:77], v[76:77], v[76:77]
	v_pk_mul_f32 v[78:79], v[78:79], v[78:79]
	v_pk_mul_f32 v[72:73], v[72:73], v[72:73]
	v_pk_mul_f32 v[74:75], v[74:75], v[74:75]
	v_pk_mul_f32 v[68:69], v[68:69], v[68:69]
	v_pk_mul_f32 v[70:71], v[70:71], v[70:71]
	v_pk_mul_f32 v[64:65], v[64:65], v[64:65]
	v_pk_mul_f32 v[66:67], v[66:67], v[66:67]
	v_pk_mul_f32 v[60:61], v[60:61], v[60:61]
	v_pk_mul_f32 v[62:63], v[62:63], v[62:63]
	v_pk_mul_f32 v[56:57], v[56:57], v[56:57]
	v_pk_mul_f32 v[58:59], v[58:59], v[58:59]
	v_pk_mul_f32 v[52:53], v[52:53], v[52:53]
	v_pk_mul_f32 v[54:55], v[54:55], v[54:55]
	v_pk_mul_f32 v[48:49], v[48:49], v[48:49]
	v_pk_mul_f32 v[50:51], v[50:51], v[50:51]
	v_pk_mul_f32 v[44:45], v[44:45], v[44:45]
	v_pk_mul_f32 v[46:47], v[46:47], v[46:47]
; template <bool RELU2>
; DI void phase_gemm_plain(const bf16_t* X, int K, const bf16_t* W, int N, bf16_t* out, char* lds) {
;     ...
;           for (int q = 0; q < 2; ++q) {
;             float a = acc[ai][bj][m][q][0], b = acc[ai][bj][m][q][1], c = acc[ai][bj][m][q][2], d = acc[ai][bj][m][q][3];
;             if (RELU2) { a = fmaxf(a, 0.f); a *= a; b = fmaxf(b, 0.f); b *= b; c = fmaxf(c, 0.f); c *= c; d = fmaxf(d, 0.f); d *= d; }
;             const int tok = mt * 256 + bj * 128 + wc * 32 + q * 16 + fr, n = nt * 256 + ai * 128 + wr * 64 + m * 16 + fq * 4;
;             store_bf4(out + (size_t)tok * N + n, a, b, c, d);
;           }
	v_pk_mul_f32 v[40:41], v[40:41], v[40:41]
	v_pk_mul_f32 v[42:43], v[42:43], v[42:43]
	v_pk_mul_f32 v[36:37], v[36:37], v[36:37]
	v_pk_mul_f32 v[38:39], v[38:39], v[38:39]
	v_pk_mul_f32 v[32:33], v[32:33], v[32:33]
	v_pk_mul_f32 v[34:35], v[34:35], v[34:35]
	v_pk_mul_f32 v[28:29], v[28:29], v[28:29]
	v_pk_mul_f32 v[30:31], v[30:31], v[30:31]
	v_pk_mul_f32 v[24:25], v[24:25], v[24:25]
	v_pk_mul_f32 v[26:27], v[26:27], v[26:27]
	v_pk_mul_f32 v[20:21], v[20:21], v[20:21]
	v_pk_mul_f32 v[22:23], v[22:23], v[22:23]
	v_pk_mul_f32 v[16:17], v[16:17], v[16:17]
	v_pk_mul_f32 v[18:19], v[18:19], v[18:19]
	v_pk_mul_f32 v[12:13], v[12:13], v[12:13]
	v_pk_mul_f32 v[14:15], v[14:15], v[14:15]
	v_pk_mul_f32 v[8:9], v[8:9], v[8:9]
	v_pk_mul_f32 v[10:11], v[10:11], v[10:11]
	v_pk_mul_f32 v[4:5], v[4:5], v[4:5]
	v_pk_mul_f32 v[6:7], v[6:7], v[6:7]
	v_pk_mul_f32 v[0:1], v[0:1], v[0:1]
	v_pk_mul_f32 v[2:3], v[2:3], v[2:3]
	s_add_i32 s0, s0, s16
	v_lshl_add_u64 v[124:125], v[130:131], 0, v[124:125]
	v_cvt_pk_bf16_f32 v126, v126, v127
	v_cvt_pk_bf16_f32 v127, v122, v123
	v_cvt_pk_bf16_f32 v116, v116, v117
	v_cvt_pk_bf16_f32 v117, v118, v119
	v_cvt_pk_bf16_f32 v112, v112, v113
	v_cvt_pk_bf16_f32 v113, v114, v115
	v_cvt_pk_bf16_f32 v108, v108, v109
	v_cvt_pk_bf16_f32 v109, v110, v111
	v_cvt_pk_bf16_f32 v104, v104, v105
	v_cvt_pk_bf16_f32 v105, v106, v107
	v_cvt_pk_bf16_f32 v100, v100, v101
	v_cvt_pk_bf16_f32 v101, v102, v103
	v_lshl_add_u64 v[92:93], v[130:131], 0, v[92:93]
	v_cvt_pk_bf16_f32 v96, v98, v99
	v_lshl_add_u64 v[88:89], v[130:131], 0, v[88:89]
	v_cvt_pk_bf16_f32 v94, v94, v95
	v_cvt_pk_bf16_f32 v95, v90, v91
	v_cvt_pk_bf16_f32 v84, v84, v85
	v_cvt_pk_bf16_f32 v85, v86, v87
	v_cvt_pk_bf16_f32 v80, v80, v81
	v_cvt_pk_bf16_f32 v81, v82, v83
	v_cvt_pk_bf16_f32 v76, v76, v77
	v_cvt_pk_bf16_f32 v77, v78, v79
	v_cvt_pk_bf16_f32 v72, v72, v73
	v_cvt_pk_bf16_f32 v73, v74, v75
	v_cvt_pk_bf16_f32 v68, v68, v69
	v_cvt_pk_bf16_f32 v69, v70, v71
	v_cvt_pk_bf16_f32 v64, v64, v65
	v_cvt_pk_bf16_f32 v65, v66, v67
	v_cvt_pk_bf16_f32 v60, v60, v61
	v_cvt_pk_bf16_f32 v61, v62, v63
	v_cvt_pk_bf16_f32 v56, v56, v57
	v_cvt_pk_bf16_f32 v57, v58, v59
	v_cvt_pk_bf16_f32 v52, v52, v53
	v_cvt_pk_bf16_f32 v53, v54, v55
	v_cvt_pk_bf16_f32 v48, v48, v49
	v_cvt_pk_bf16_f32 v49, v50, v51
	v_cvt_pk_bf16_f32 v44, v44, v45
	v_cvt_pk_bf16_f32 v45, v46, v47
	v_cvt_pk_bf16_f32 v40, v40, v41
	v_cvt_pk_bf16_f32 v41, v42, v43
	v_cvt_pk_bf16_f32 v36, v36, v37
	v_cvt_pk_bf16_f32 v37, v38, v39
	v_cvt_pk_bf16_f32 v32, v32, v33
	v_cvt_pk_bf16_f32 v33, v34, v35
	v_cvt_pk_bf16_f32 v28, v28, v29
	v_cvt_pk_bf16_f32 v29, v30, v31
	v_cvt_pk_bf16_f32 v24, v24, v25
	v_cvt_pk_bf16_f32 v25, v26, v27
	v_cvt_pk_bf16_f32 v20, v20, v21
	v_cvt_pk_bf16_f32 v21, v22, v23
	v_cvt_pk_bf16_f32 v16, v16, v17
	v_cvt_pk_bf16_f32 v17, v18, v19
	v_cvt_pk_bf16_f32 v12, v12, v13
	v_cvt_pk_bf16_f32 v13, v14, v15
	v_cvt_pk_bf16_f32 v8, v8, v9
	v_cvt_pk_bf16_f32 v9, v10, v11
	v_cvt_pk_bf16_f32 v4, v4, v5
	v_cvt_pk_bf16_f32 v5, v6, v7
	v_cvt_pk_bf16_f32 v0, v0, v1
	v_cvt_pk_bf16_f32 v1, v2, v3
	s_cmpk_lt_i32 s0, 0x800
	ds_write_b64 v190, v[132:133]
	ds_write_b64 v191, v[126:127]
	ds_write_b64 v190, v[116:117] offset:32
	ds_write_b64 v191, v[112:113] offset:32
	ds_write_b64 v190, v[108:109] offset:64
	ds_write_b64 v191, v[104:105] offset:64
	ds_write_b64 v190, v[100:101] offset:96
	ds_write_b64 v192, v[96:97]
	ds_write_b64 v193, v[94:95]
	ds_write_b64 v192, v[84:85] offset:32
	ds_write_b64 v193, v[80:81] offset:32
	ds_write_b64 v192, v[76:77] offset:64
	ds_write_b64 v193, v[72:73] offset:64
	ds_write_b64 v192, v[68:69] offset:96
	ds_write_b64 v193, v[64:65] offset:96
	ds_write_b64 v190, v[60:61] offset:256
	ds_write_b64 v191, v[56:57] offset:256
	ds_write_b64 v190, v[52:53] offset:288
	ds_write_b64 v191, v[48:49] offset:288
	ds_write_b64 v190, v[44:45] offset:320
	ds_write_b64 v191, v[40:41] offset:320
	ds_write_b64 v190, v[36:37] offset:352
	ds_write_b64 v191, v[32:33] offset:352
	ds_write_b64 v192, v[28:29] offset:256
	ds_write_b64 v193, v[24:25] offset:256
	ds_write_b64 v192, v[20:21] offset:288
	ds_write_b64 v193, v[16:17] offset:288
	ds_write_b64 v192, v[12:13] offset:320
	ds_write_b64 v193, v[8:9] offset:320
	ds_write_b64 v192, v[4:5] offset:352
	ds_write_b64 v193, v[0:1] offset:352
	s_waitcnt lgkmcnt(0)
	s_barrier
	ds_read_b128 v[0:3], v194
	ds_read_b128 v[4:7], v194 offset:1056
	ds_read_b128 v[8:11], v194 offset:2112
	ds_read_b128 v[12:15], v194 offset:3168
	ds_read_b128 v[16:19], v194 offset:4224
	ds_read_b128 v[20:23], v194 offset:5280
	ds_read_b128 v[24:27], v194 offset:6336
	ds_read_b128 v[28:31], v194 offset:7392
	ds_read_b128 v[32:35], v194 offset:8448
	ds_read_b128 v[36:39], v194 offset:9504
	ds_read_b128 v[40:43], v194 offset:10560
	ds_read_b128 v[44:47], v194 offset:11616
	ds_read_b128 v[48:51], v194 offset:12672
	ds_read_b128 v[52:55], v194 offset:13728
	ds_read_b128 v[56:59], v194 offset:14784
	ds_read_b128 v[60:63], v194 offset:15840
	s_waitcnt lgkmcnt(0)
	s_barrier
	global_store_dwordx4 v[196:197], v[0:3], off
	v_lshl_add_u64 v[196:197], v[196:197], 0, s[24:25]
	global_store_dwordx4 v[196:197], v[4:7], off
	v_lshl_add_u64 v[196:197], v[196:197], 0, s[24:25]
	global_store_dwordx4 v[196:197], v[8:11], off
	v_lshl_add_u64 v[196:197], v[196:197], 0, s[24:25]
	global_store_dwordx4 v[196:197], v[12:15], off
	v_lshl_add_u64 v[196:197], v[196:197], 0, s[24:25]
	global_store_dwordx4 v[196:197], v[16:19], off
	v_lshl_add_u64 v[196:197], v[196:197], 0, s[24:25]
	global_store_dwordx4 v[196:197], v[20:23], off
	v_lshl_add_u64 v[196:197], v[196:197], 0, s[24:25]
	global_store_dwordx4 v[196:197], v[24:27], off
	v_lshl_add_u64 v[196:197], v[196:197], 0, s[24:25]
	global_store_dwordx4 v[196:197], v[28:31], off
	v_lshl_add_u64 v[196:197], v[196:197], 0, s[24:25]
	global_store_dwordx4 v[196:197], v[32:35], off
	v_lshl_add_u64 v[196:197], v[196:197], 0, s[24:25]
	global_store_dwordx4 v[196:197], v[36:39], off
	v_lshl_add_u64 v[196:197], v[196:197], 0, s[24:25]
	global_store_dwordx4 v[196:197], v[40:43], off
	v_lshl_add_u64 v[196:197], v[196:197], 0, s[24:25]
	global_store_dwordx4 v[196:197], v[44:47], off
	v_lshl_add_u64 v[196:197], v[196:197], 0, s[24:25]
	global_store_dwordx4 v[196:197], v[48:51], off
	v_lshl_add_u64 v[196:197], v[196:197], 0, s[24:25]
	global_store_dwordx4 v[196:197], v[52:55], off
	v_lshl_add_u64 v[196:197], v[196:197], 0, s[24:25]
	global_store_dwordx4 v[196:197], v[56:59], off
	v_lshl_add_u64 v[196:197], v[196:197], 0, s[24:25]
	global_store_dwordx4 v[196:197], v[60:63], off
	s_cbranch_scc0 .LBB0_337
